# mprep conv: both 8-row halves' row loads issued before computing (one round trip per pass instead of two); on top of v64
# baseline (speedup 1.0000x reference)
.Lpadskip_1:
	s_branch .Lpadskip_3
	s_nop 0
	s_nop 0
	s_nop 0
	s_nop 0
	s_nop 0
	s_nop 0
	s_nop 0
	s_nop 0
	s_nop 0
	s_nop 0
	s_nop 0
	s_nop 0
	s_nop 0
	s_nop 0
	s_nop 0
	s_nop 0
	s_nop 0
	s_nop 0
	s_nop 0
	s_nop 0
	s_nop 0
	s_nop 0
	s_nop 0
	s_nop 0
	s_nop 0
	s_nop 0
	s_nop 0
	s_nop 0
	s_nop 0
	s_nop 0
	s_nop 0
	s_nop 0
	s_nop 0
	s_nop 0
	s_nop 0
	s_nop 0
	s_nop 0
	s_nop 0
	s_nop 0
	s_nop 0
	s_nop 0
	s_nop 0
	s_nop 0
	s_nop 0
	s_nop 0
	s_nop 0
	s_nop 0
	s_nop 0
	s_nop 0
	s_nop 0
	s_nop 0
	s_nop 0
	s_nop 0
	s_nop 0
	s_nop 0
	s_nop 0
	s_nop 0
	s_nop 0
	s_nop 0
.Lpadskip_3:
	s_branch .Lpadskip_4
	s_nop 0
	s_nop 0
	s_nop 0
	s_nop 0
	s_nop 0
	s_nop 0
	s_nop 0
	s_nop 0
	s_nop 0
	s_nop 0
.Lpadskip_4:
.LBB0_402:
	s_add_i32 s36, s93, s33
	s_lshl_b32 s3, s3, 12
	v_lshl_add_u64 v[16:17], v[12:13], 0, s[70:71]
	s_mov_b32 m0, s36
	s_add_i32 s19, s36, 0x2000
	s_lshl_b32 s10, s2, 13
	s_and_b32 s11, s3, 0x3000
	s_waitcnt vmcnt(4)
	s_barrier
	global_load_lds_dwordx4 v[16:17], off
	v_lshl_add_u64 v[16:17], v[10:11], 0, s[70:71]
	s_mov_b32 m0, s19
	s_add_i32 s16, s41, 0x8000
	s_add_i32 s15, s41, 0xa000
	global_load_lds_dwordx4 v[16:17], off
	v_lshl_add_u64 v[16:17], v[6:7], 0, s[70:71]
	s_mov_b32 m0, s16
	s_add_u32 s6, s4, 0x10080
	global_load_lds_dwordx4 v[16:17], off
	v_lshl_add_u64 v[16:17], v[8:9], 0, s[70:71]
	s_mov_b32 m0, s15
	s_addc_u32 s7, s5, 0
	s_add_i32 s2, s94, s33
	global_load_lds_dwordx4 v[16:17], off
	v_lshl_add_u64 v[16:17], s[6:7], 0, v[128:129]
	s_mov_b32 m0, s2
	s_add_i32 s3, s2, 0x2000
	global_load_lds_dwordx4 v[16:17], off
	v_lshl_add_u64 v[16:17], s[6:7], 0, v[4:5]
	s_mov_b32 m0, s3
	v_and_b32_e32 v15, 15, v14
	global_load_lds_dwordx4 v[16:17], off
	v_and_b32_e32 v16, 48, v14
	v_lshlrev_b32_e32 v14, 2, v14
	v_lshlrev_b32_e32 v15, 6, v15
	v_and_b32_e32 v14, 32, v14
	v_or_b32_e32 v17, v15, v16
	v_bitop3_b32 v15, v15, v14, v16 bitop3:0x36
	v_or_b32_e32 v64, s11, v15
	s_add_i32 s43, 0, 0x10000
	v_bitop3_b32 v14, v17, s10, v14 bitop3:0xde
	v_add_u32_e32 v131, s43, v64
	s_waitcnt vmcnt(6)
	s_barrier
	s_add_u32 s48, s8, 0x10080
	v_add_u32_e32 v183, 0, v14
	ds_read_b128 v[14:17], v131
	ds_read_b128 v[18:21], v131 offset:1024
	ds_read_b128 v[22:25], v131 offset:2048
	ds_read_b128 v[26:29], v131 offset:3072
	s_addc_u32 s49, s9, 0
	s_add_i32 s50, 0, 0x14000
	s_add_u32 s12, s4, 0x10100
	s_addc_u32 s13, s5, 0
	s_add_u32 s10, s8, 0x10100
	s_addc_u32 s11, s9, 0
	s_add_u32 s6, s4, 0x10180
	v_add_u32_e32 v144, s50, v64
	s_addc_u32 s7, s5, 0
	s_add_i32 s17, s41, 0xc000
	v_lshl_add_u64 v[62:63], s[48:49], 0, v[0:1]
	s_mov_b32 m0, s17
	s_add_i32 s14, s41, 0xe000
	ds_read_b128 v[30:33], v183
	ds_read_b128 v[34:37], v183 offset:1024
	ds_read_b128 v[38:41], v183 offset:2048
	ds_read_b128 v[42:45], v183 offset:3072
	ds_read_b128 v[46:49], v183 offset:4096
	ds_read_b128 v[50:53], v183 offset:5120
	ds_read_b128 v[54:57], v183 offset:6144
	ds_read_b128 v[58:61], v183 offset:7168
	global_load_lds_dwordx4 v[62:63], off
	v_lshl_add_u64 v[62:63], s[48:49], 0, v[2:3]
	s_mov_b32 m0, s14
	v_add_u32_e32 v145, s93, v64
	global_load_lds_dwordx4 v[62:63], off
	s_waitcnt lgkmcnt(8)
	s_barrier
	s_waitcnt lgkmcnt(0)
	v_add_u32_e32 v146, s94, v64
	s_setprio 1
	s_waitcnt lgkmcnt(0)
	v_mfma_f32_16x16x32_bf16 v[62:65], v[14:17], v[30:33], 0
	v_mfma_f32_16x16x32_bf16 v[66:69], v[22:25], v[30:33], 0
	v_mfma_f32_16x16x32_bf16 v[70:73], v[14:17], v[38:41], 0
	v_mfma_f32_16x16x32_bf16 v[74:77], v[22:25], v[38:41], 0
	v_mfma_f32_16x16x32_bf16 v[78:81], v[14:17], v[46:49], 0
	v_mfma_f32_16x16x32_bf16 v[82:85], v[22:25], v[46:49], 0
	v_mfma_f32_16x16x32_bf16 v[86:89], v[14:17], v[54:57], 0
	v_mfma_f32_16x16x32_bf16 v[90:93], v[22:25], v[54:57], 0
	v_mfma_f32_16x16x32_bf16 v[62:65], v[18:21], v[34:37], v[62:65]
	v_mfma_f32_16x16x32_bf16 v[66:69], v[26:29], v[34:37], v[66:69]
	v_mfma_f32_16x16x32_bf16 v[70:73], v[18:21], v[42:45], v[70:73]
	v_mfma_f32_16x16x32_bf16 v[74:77], v[26:29], v[42:45], v[74:77]
	v_mfma_f32_16x16x32_bf16 v[78:81], v[18:21], v[50:53], v[78:81]
	v_mfma_f32_16x16x32_bf16 v[82:85], v[26:29], v[50:53], v[82:85]
	v_mfma_f32_16x16x32_bf16 v[86:89], v[18:21], v[58:61], v[86:89]
	v_mfma_f32_16x16x32_bf16 v[90:93], v[26:29], v[58:61], v[90:93]
	s_setprio 0
	s_barrier
	s_add_i32 s43, s43, s33
	v_lshl_add_u64 v[110:111], v[12:13], 0, s[72:73]
	s_mov_b32 m0, s43
	ds_read_b128 v[94:97], v144
	ds_read_b128 v[98:101], v144 offset:1024
	ds_read_b128 v[102:105], v144 offset:2048
	ds_read_b128 v[106:109], v144 offset:3072
	global_load_lds_dwordx4 v[110:111], off
	v_lshl_add_u64 v[110:111], v[10:11], 0, s[72:73]
	s_add_i32 m0, s43, 0x2000
	s_nop 0
	global_load_lds_dwordx4 v[110:111], off
	s_barrier
	s_waitcnt lgkmcnt(0)
	s_setprio 1
	s_waitcnt lgkmcnt(0)
	v_mfma_f32_16x16x32_bf16 v[110:113], v[94:97], v[30:33], 0
	v_mfma_f32_16x16x32_bf16 v[30:33], v[102:105], v[30:33], 0
	v_mfma_f32_16x16x32_bf16 v[110:113], v[98:101], v[34:37], v[110:113]
	v_mfma_f32_16x16x32_bf16 v[30:33], v[106:109], v[34:37], v[30:33]
	v_mfma_f32_16x16x32_bf16 v[34:37], v[94:97], v[38:41], 0
	v_mfma_f32_16x16x32_bf16 v[38:41], v[102:105], v[38:41], 0
	v_mfma_f32_16x16x32_bf16 v[34:37], v[98:101], v[42:45], v[34:37]
	v_mfma_f32_16x16x32_bf16 v[38:41], v[106:109], v[42:45], v[38:41]
	v_mfma_f32_16x16x32_bf16 v[42:45], v[94:97], v[46:49], 0
	v_mfma_f32_16x16x32_bf16 v[46:49], v[102:105], v[46:49], 0
	v_mfma_f32_16x16x32_bf16 v[42:45], v[98:101], v[50:53], v[42:45]
	v_mfma_f32_16x16x32_bf16 v[46:49], v[106:109], v[50:53], v[46:49]
	v_mfma_f32_16x16x32_bf16 v[50:53], v[94:97], v[54:57], 0
	v_mfma_f32_16x16x32_bf16 v[54:57], v[102:105], v[54:57], 0
	v_mfma_f32_16x16x32_bf16 v[50:53], v[98:101], v[58:61], v[50:53]
	v_mfma_f32_16x16x32_bf16 v[54:57], v[106:109], v[58:61], v[54:57]
	s_setprio 0
	s_mov_b32 m0, s41
	v_lshl_add_u64 v[126:127], v[6:7], 0, s[72:73]
	s_barrier
	ds_read_b128 v[58:61], v183 offset:16384
	ds_read_b128 v[114:117], v183 offset:17408
	ds_read_b128 v[118:121], v183 offset:18432
	ds_read_b128 v[122:125], v183 offset:19456
	ds_read_b128 v[132:135], v183 offset:20480
	ds_read_b128 v[136:139], v183 offset:21504
	ds_read_b128 v[140:143], v183 offset:22528
	ds_read_b128 v[152:155], v183 offset:23552
	global_load_lds_dwordx4 v[126:127], off
	v_lshl_add_u64 v[126:127], v[8:9], 0, s[72:73]
	s_mov_b32 m0, s42
	s_nop 0
	global_load_lds_dwordx4 v[126:127], off
	s_barrier
	s_waitcnt lgkmcnt(0)
	s_setprio 1
	s_waitcnt lgkmcnt(0)
	v_mfma_f32_16x16x32_bf16 v[156:159], v[14:17], v[58:61], 0
	v_mfma_f32_16x16x32_bf16 v[164:167], v[14:17], v[118:121], 0
	v_mfma_f32_16x16x32_bf16 v[172:175], v[14:17], v[132:135], 0
	v_mfma_f32_16x16x32_bf16 v[14:17], v[14:17], v[140:143], 0
	v_mfma_f32_16x16x32_bf16 v[156:159], v[18:21], v[114:117], v[156:159]
	v_mfma_f32_16x16x32_bf16 v[164:167], v[18:21], v[122:125], v[164:167]
	v_mfma_f32_16x16x32_bf16 v[172:175], v[18:21], v[136:139], v[172:175]
	v_mfma_f32_16x16x32_bf16 v[14:17], v[18:21], v[152:155], v[14:17]
	v_mfma_f32_16x16x32_bf16 v[18:21], v[22:25], v[140:143], 0
	v_mfma_f32_16x16x32_bf16 v[160:163], v[22:25], v[58:61], 0
	v_mfma_f32_16x16x32_bf16 v[168:171], v[22:25], v[118:121], 0
	v_mfma_f32_16x16x32_bf16 v[176:179], v[22:25], v[132:135], 0
	v_mfma_f32_16x16x32_bf16 v[18:21], v[26:29], v[152:155], v[18:21]
	v_mfma_f32_16x16x32_bf16 v[160:163], v[26:29], v[114:117], v[160:163]
	v_mfma_f32_16x16x32_bf16 v[168:171], v[26:29], v[122:125], v[168:171]
	v_mfma_f32_16x16x32_bf16 v[176:179], v[26:29], v[136:139], v[176:179]
	s_setprio 0
	s_barrier
	s_add_i32 s33, s50, s33
	v_lshl_add_u64 v[22:23], s[12:13], 0, v[128:129]
	s_mov_b32 m0, s33
	s_nop 0
	global_load_lds_dwordx4 v[22:23], off
	v_lshl_add_u64 v[22:23], s[12:13], 0, v[4:5]
	s_add_i32 m0, s33, 0x2000
	s_nop 0
	global_load_lds_dwordx4 v[22:23], off
	s_waitcnt vmcnt(6)
	s_barrier
	s_setprio 1
	v_mfma_f32_16x16x32_bf16 v[22:25], v[94:97], v[58:61], 0
	v_mfma_f32_16x16x32_bf16 v[26:29], v[102:105], v[58:61], 0
	v_mfma_f32_16x16x32_bf16 v[22:25], v[98:101], v[114:117], v[22:25]
	v_mfma_f32_16x16x32_bf16 v[26:29], v[106:109], v[114:117], v[26:29]
	v_mfma_f32_16x16x32_bf16 v[58:61], v[94:97], v[118:121], 0
	v_mfma_f32_16x16x32_bf16 v[114:117], v[102:105], v[118:121], 0
	v_mfma_f32_16x16x32_bf16 v[118:121], v[94:97], v[132:135], 0
	v_mfma_f32_16x16x32_bf16 v[94:97], v[94:97], v[140:143], 0
	v_mfma_f32_16x16x32_bf16 v[58:61], v[98:101], v[122:125], v[58:61]
	v_mfma_f32_16x16x32_bf16 v[114:117], v[106:109], v[122:125], v[114:117]
	v_mfma_f32_16x16x32_bf16 v[118:121], v[98:101], v[136:139], v[118:121]
	v_mfma_f32_16x16x32_bf16 v[122:125], v[102:105], v[132:135], 0
	v_mfma_f32_16x16x32_bf16 v[94:97], v[98:101], v[152:155], v[94:97]
	v_mfma_f32_16x16x32_bf16 v[98:101], v[102:105], v[140:143], 0
	v_mfma_f32_16x16x32_bf16 v[122:125], v[106:109], v[136:139], v[122:125]
	v_mfma_f32_16x16x32_bf16 v[98:101], v[106:109], v[152:155], v[98:101]
	s_setprio 0
	s_barrier
	ds_read_b128 v[102:105], v145
	ds_read_b128 v[106:109], v145 offset:1024
	ds_read_b128 v[132:135], v145 offset:2048
	ds_read_b128 v[136:139], v145 offset:3072
	s_mov_b32 m0, s40
	v_lshl_add_u64 v[126:127], s[10:11], 0, v[0:1]
	ds_read_b128 v[140:143], v183 offset:32768
	ds_read_b128 v[152:155], v183 offset:33792
	ds_read_b128 v[184:187], v183 offset:34816
	ds_read_b128 v[188:191], v183 offset:35840
	ds_read_b128 v[192:195], v183 offset:36864
	ds_read_b128 v[196:199], v183 offset:37888
	ds_read_b128 v[200:203], v183 offset:38912
	ds_read_b128 v[204:207], v183 offset:39936
	global_load_lds_dwordx4 v[126:127], off
	v_lshl_add_u64 v[126:127], s[10:11], 0, v[2:3]
	s_mov_b32 m0, s18
	s_nop 0
	global_load_lds_dwordx4 v[126:127], off
	s_waitcnt lgkmcnt(8)
	s_barrier
	s_waitcnt lgkmcnt(0)
	s_setprio 1
	s_waitcnt lgkmcnt(0)
	v_mfma_f32_16x16x32_bf16 v[62:65], v[102:105], v[140:143], v[62:65]
	v_mfma_f32_16x16x32_bf16 v[66:69], v[132:135], v[140:143], v[66:69]
	v_mfma_f32_16x16x32_bf16 v[70:73], v[102:105], v[184:187], v[70:73]
	v_mfma_f32_16x16x32_bf16 v[74:77], v[132:135], v[184:187], v[74:77]
	v_mfma_f32_16x16x32_bf16 v[78:81], v[102:105], v[192:195], v[78:81]
	v_mfma_f32_16x16x32_bf16 v[82:85], v[132:135], v[192:195], v[82:85]
	v_mfma_f32_16x16x32_bf16 v[86:89], v[102:105], v[200:203], v[86:89]
	v_mfma_f32_16x16x32_bf16 v[90:93], v[132:135], v[200:203], v[90:93]
	v_mfma_f32_16x16x32_bf16 v[62:65], v[106:109], v[152:155], v[62:65]
	v_mfma_f32_16x16x32_bf16 v[66:69], v[136:139], v[152:155], v[66:69]
	v_mfma_f32_16x16x32_bf16 v[70:73], v[106:109], v[188:191], v[70:73]
	v_mfma_f32_16x16x32_bf16 v[74:77], v[136:139], v[188:191], v[74:77]
	v_mfma_f32_16x16x32_bf16 v[78:81], v[106:109], v[196:199], v[78:81]
	v_mfma_f32_16x16x32_bf16 v[82:85], v[136:139], v[196:199], v[82:85]
	v_mfma_f32_16x16x32_bf16 v[86:89], v[106:109], v[204:207], v[86:89]
	v_mfma_f32_16x16x32_bf16 v[90:93], v[136:139], v[204:207], v[90:93]
	s_setprio 0
	s_barrier
	s_mov_b32 m0, s36
	v_lshl_add_u64 v[12:13], v[12:13], 0, s[76:77]
	ds_read_b128 v[208:211], v146
	ds_read_b128 v[212:215], v146 offset:1024
	ds_read_b128 v[216:219], v146 offset:2048
	ds_read_b128 v[220:223], v146 offset:3072
	global_load_lds_dwordx4 v[12:13], off
	v_lshl_add_u64 v[10:11], v[10:11], 0, s[76:77]
	s_mov_b32 m0, s19
	s_nop 0
	global_load_lds_dwordx4 v[10:11], off
	s_barrier
	s_waitcnt lgkmcnt(0)
	s_setprio 1
	s_waitcnt lgkmcnt(0)
	v_mfma_f32_16x16x32_bf16 v[10:13], v[208:211], v[140:143], v[110:113]
	v_mfma_f32_16x16x32_bf16 v[30:33], v[216:219], v[140:143], v[30:33]
	v_mfma_f32_16x16x32_bf16 v[34:37], v[208:211], v[184:187], v[34:37]
	v_mfma_f32_16x16x32_bf16 v[38:41], v[216:219], v[184:187], v[38:41]
	v_mfma_f32_16x16x32_bf16 v[42:45], v[208:211], v[192:195], v[42:45]
	v_mfma_f32_16x16x32_bf16 v[46:49], v[216:219], v[192:195], v[46:49]
	v_mfma_f32_16x16x32_bf16 v[50:53], v[208:211], v[200:203], v[50:53]
	v_mfma_f32_16x16x32_bf16 v[54:57], v[216:219], v[200:203], v[54:57]
	v_mfma_f32_16x16x32_bf16 v[10:13], v[212:215], v[152:155], v[10:13]
	v_mfma_f32_16x16x32_bf16 v[30:33], v[220:223], v[152:155], v[30:33]
	v_mfma_f32_16x16x32_bf16 v[34:37], v[212:215], v[188:191], v[34:37]
	v_mfma_f32_16x16x32_bf16 v[38:41], v[220:223], v[188:191], v[38:41]
	v_mfma_f32_16x16x32_bf16 v[42:45], v[212:215], v[196:199], v[42:45]
	v_mfma_f32_16x16x32_bf16 v[46:49], v[220:223], v[196:199], v[46:49]
	v_mfma_f32_16x16x32_bf16 v[50:53], v[212:215], v[204:207], v[50:53]
	v_mfma_f32_16x16x32_bf16 v[54:57], v[220:223], v[204:207], v[54:57]
	s_setprio 0
	s_mov_b32 m0, s16
	v_lshl_add_u64 v[6:7], v[6:7], 0, s[76:77]
	s_barrier
	ds_read_b128 v[110:113], v183 offset:49152
	ds_read_b128 v[140:143], v183 offset:50176
	ds_read_b128 v[152:155], v183 offset:51200
	ds_read_b128 v[184:187], v183 offset:52224
	ds_read_b128 v[188:191], v183 offset:53248
	ds_read_b128 v[192:195], v183 offset:54272
	ds_read_b128 v[196:199], v183 offset:55296
	ds_read_b128 v[200:203], v183 offset:56320
	global_load_lds_dwordx4 v[6:7], off
	v_lshl_add_u64 v[6:7], v[8:9], 0, s[76:77]
	s_mov_b32 m0, s15
	s_nop 0
	global_load_lds_dwordx4 v[6:7], off
	s_barrier
	s_waitcnt lgkmcnt(0)
	s_setprio 1
	s_waitcnt lgkmcnt(0)
	v_mfma_f32_16x16x32_bf16 v[6:9], v[102:105], v[110:113], v[156:159]
	v_mfma_f32_16x16x32_bf16 v[14:17], v[102:105], v[196:199], v[14:17]
	v_mfma_f32_16x16x32_bf16 v[18:21], v[132:135], v[196:199], v[18:21]
	v_mfma_f32_16x16x32_bf16 v[6:9], v[106:109], v[140:143], v[6:9]
	v_mfma_f32_16x16x32_bf16 v[156:159], v[132:135], v[110:113], v[160:163]
	v_mfma_f32_16x16x32_bf16 v[160:163], v[102:105], v[152:155], v[164:167]
	v_mfma_f32_16x16x32_bf16 v[164:167], v[132:135], v[152:155], v[168:171]
	v_mfma_f32_16x16x32_bf16 v[168:171], v[102:105], v[188:191], v[172:175]
	v_mfma_f32_16x16x32_bf16 v[172:175], v[132:135], v[188:191], v[176:179]
	v_mfma_f32_16x16x32_bf16 v[14:17], v[106:109], v[200:203], v[14:17]
	v_mfma_f32_16x16x32_bf16 v[18:21], v[136:139], v[200:203], v[18:21]
	v_mfma_f32_16x16x32_bf16 v[156:159], v[136:139], v[140:143], v[156:159]
	v_mfma_f32_16x16x32_bf16 v[160:163], v[106:109], v[184:187], v[160:163]
	v_mfma_f32_16x16x32_bf16 v[164:167], v[136:139], v[184:187], v[164:167]
	v_mfma_f32_16x16x32_bf16 v[168:171], v[106:109], v[192:195], v[168:171]
	v_mfma_f32_16x16x32_bf16 v[172:175], v[136:139], v[192:195], v[172:175]
	s_setprio 0
	s_barrier
	s_mov_b32 m0, s2
	v_lshl_add_u64 v[102:103], s[6:7], 0, v[128:129]
	global_load_lds_dwordx4 v[102:103], off
	v_lshl_add_u64 v[4:5], s[6:7], 0, v[4:5]
	s_mov_b32 m0, s3
	s_nop 0
	global_load_lds_dwordx4 v[4:5], off
	s_waitcnt vmcnt(6)
	s_barrier
	s_setprio 1
	v_mfma_f32_16x16x32_bf16 v[22:25], v[208:211], v[110:113], v[22:25]
	v_mfma_f32_16x16x32_bf16 v[26:29], v[216:219], v[110:113], v[26:29]
	v_mfma_f32_16x16x32_bf16 v[58:61], v[208:211], v[152:155], v[58:61]
	v_mfma_f32_16x16x32_bf16 v[102:105], v[216:219], v[152:155], v[114:117]
	v_mfma_f32_16x16x32_bf16 v[106:109], v[208:211], v[188:191], v[118:121]
	v_mfma_f32_16x16x32_bf16 v[110:113], v[216:219], v[188:191], v[122:125]
	v_mfma_f32_16x16x32_bf16 v[94:97], v[208:211], v[196:199], v[94:97]
	v_mfma_f32_16x16x32_bf16 v[98:101], v[216:219], v[196:199], v[98:101]
	v_mfma_f32_16x16x32_bf16 v[22:25], v[212:215], v[140:143], v[22:25]
	v_mfma_f32_16x16x32_bf16 v[26:29], v[220:223], v[140:143], v[26:29]
	v_mfma_f32_16x16x32_bf16 v[58:61], v[212:215], v[184:187], v[58:61]
	v_mfma_f32_16x16x32_bf16 v[102:105], v[220:223], v[184:187], v[102:105]
	v_mfma_f32_16x16x32_bf16 v[106:109], v[212:215], v[192:195], v[106:109]
	v_mfma_f32_16x16x32_bf16 v[110:113], v[220:223], v[192:195], v[110:113]
	v_mfma_f32_16x16x32_bf16 v[94:97], v[212:215], v[200:203], v[94:97]
	v_mfma_f32_16x16x32_bf16 v[98:101], v[220:223], v[200:203], v[98:101]
	s_setprio 0
	s_add_u32 s2, s8, 0x10180
	s_addc_u32 s3, s9, 0
	s_mov_b32 m0, s17
	v_lshl_add_u64 v[0:1], s[2:3], 0, v[0:1]
	s_barrier
	ds_read_b128 v[114:117], v131
	ds_read_b128 v[118:121], v131 offset:1024
	ds_read_b128 v[122:125], v131 offset:2048
	ds_read_b128 v[132:135], v131 offset:3072
	ds_read_b128 v[136:139], v183
	ds_read_b128 v[140:143], v183 offset:1024
	ds_read_b128 v[152:155], v183 offset:2048
	ds_read_b128 v[176:179], v183 offset:3072
	ds_read_b128 v[184:187], v183 offset:4096
	ds_read_b128 v[188:191], v183 offset:5120
	ds_read_b128 v[192:195], v183 offset:6144
	ds_read_b128 v[196:199], v183 offset:7168
	global_load_lds_dwordx4 v[0:1], off
	v_lshl_add_u64 v[0:1], s[2:3], 0, v[2:3]
	s_mov_b32 m0, s14
	s_nop 0
	global_load_lds_dwordx4 v[0:1], off
	s_barrier
	s_waitcnt lgkmcnt(0)
	s_setprio 1
	s_waitcnt lgkmcnt(0)
	v_mfma_f32_16x16x32_bf16 v[0:3], v[114:117], v[136:139], v[62:65]
	v_mfma_f32_16x16x32_bf16 v[62:65], v[122:125], v[136:139], v[66:69]
	v_mfma_f32_16x16x32_bf16 v[66:69], v[114:117], v[152:155], v[70:73]
	v_mfma_f32_16x16x32_bf16 v[70:73], v[122:125], v[152:155], v[74:77]
	v_mfma_f32_16x16x32_bf16 v[74:77], v[114:117], v[184:187], v[78:81]
	v_mfma_f32_16x16x32_bf16 v[78:81], v[122:125], v[184:187], v[82:85]
	v_mfma_f32_16x16x32_bf16 v[82:85], v[114:117], v[192:195], v[86:89]
	v_mfma_f32_16x16x32_bf16 v[0:3], v[118:121], v[140:143], v[0:3]
	v_mfma_f32_16x16x32_bf16 v[62:65], v[132:135], v[140:143], v[62:65]
	v_mfma_f32_16x16x32_bf16 v[66:69], v[118:121], v[176:179], v[66:69]
	v_mfma_f32_16x16x32_bf16 v[70:73], v[132:135], v[176:179], v[70:73]
	v_mfma_f32_16x16x32_bf16 v[74:77], v[118:121], v[188:191], v[74:77]
	v_mfma_f32_16x16x32_bf16 v[78:81], v[132:135], v[188:191], v[78:81]
	v_mfma_f32_16x16x32_bf16 v[82:85], v[118:121], v[196:199], v[82:85]
	v_mfma_f32_16x16x32_bf16 v[86:89], v[122:125], v[192:195], v[90:93]
	v_mfma_f32_16x16x32_bf16 v[200:203], v[132:135], v[196:199], v[86:89]
	s_setprio 0
	s_barrier
	s_nop 4
	ds_read_b128 v[86:89], v144
	ds_read_b128 v[90:93], v144 offset:1024
	ds_read_b128 v[204:207], v144 offset:2048
	ds_read_b128 v[208:211], v144 offset:3072
	s_barrier
	s_waitcnt lgkmcnt(0)
	s_setprio 1
	s_waitcnt lgkmcnt(0)
	v_mfma_f32_16x16x32_bf16 v[30:33], v[204:207], v[136:139], v[30:33]
	v_mfma_f32_16x16x32_bf16 v[10:13], v[86:89], v[136:139], v[10:13]
	v_mfma_f32_16x16x32_bf16 v[136:139], v[208:211], v[140:143], v[30:33]
	v_mfma_f32_16x16x32_bf16 v[30:33], v[86:89], v[152:155], v[34:37]
	v_mfma_f32_16x16x32_bf16 v[10:13], v[90:93], v[140:143], v[10:13]
	v_mfma_f32_16x16x32_bf16 v[140:143], v[90:93], v[176:179], v[30:33]
	v_mfma_f32_16x16x32_bf16 v[30:33], v[204:207], v[152:155], v[38:41]
	v_mfma_f32_16x16x32_bf16 v[152:155], v[208:211], v[176:179], v[30:33]
	v_mfma_f32_16x16x32_bf16 v[30:33], v[86:89], v[184:187], v[42:45]
	v_mfma_f32_16x16x32_bf16 v[40:43], v[90:93], v[188:191], v[30:33]
	v_mfma_f32_16x16x32_bf16 v[30:33], v[204:207], v[184:187], v[46:49]
	v_mfma_f32_16x16x32_bf16 v[44:47], v[208:211], v[188:191], v[30:33]
	v_mfma_f32_16x16x32_bf16 v[30:33], v[86:89], v[192:195], v[50:53]
	v_mfma_f32_16x16x32_bf16 v[48:51], v[90:93], v[196:199], v[30:33]
	v_mfma_f32_16x16x32_bf16 v[30:33], v[204:207], v[192:195], v[54:57]
	v_mfma_f32_16x16x32_bf16 v[52:55], v[208:211], v[196:199], v[30:33]
	s_setprio 0
	s_barrier
	s_nop 4
	ds_read_b128 v[30:33], v183 offset:16384
	ds_read_b128 v[34:37], v183 offset:17408
	ds_read_b128 v[176:179], v183 offset:18432
	ds_read_b128 v[184:187], v183 offset:19456
	ds_read_b128 v[188:191], v183 offset:20480
	ds_read_b128 v[192:195], v183 offset:21504
	ds_read_b128 v[196:199], v183 offset:22528
	ds_read_b128 v[212:215], v183 offset:23552
	s_waitcnt vmcnt(4)
	s_barrier
	s_waitcnt lgkmcnt(0)
	s_setprio 1
	s_waitcnt lgkmcnt(0)
	v_mfma_f32_16x16x32_bf16 v[4:7], v[114:117], v[30:33], v[6:9]
	v_mfma_f32_16x16x32_bf16 v[14:17], v[114:117], v[196:199], v[14:17]
	v_mfma_f32_16x16x32_bf16 v[4:7], v[118:121], v[34:37], v[4:7]
	v_mfma_f32_16x16x32_bf16 v[156:159], v[122:125], v[30:33], v[156:159]
	v_mfma_f32_16x16x32_bf16 v[160:163], v[114:117], v[176:179], v[160:163]
	v_mfma_f32_16x16x32_bf16 v[164:167], v[122:125], v[176:179], v[164:167]
	v_mfma_f32_16x16x32_bf16 v[168:171], v[114:117], v[188:191], v[168:171]
	v_mfma_f32_16x16x32_bf16 v[172:175], v[122:125], v[188:191], v[172:175]
	v_mfma_f32_16x16x32_bf16 v[216:219], v[118:121], v[212:215], v[14:17]
	v_mfma_f32_16x16x32_bf16 v[14:17], v[122:125], v[196:199], v[18:21]
	v_mfma_f32_16x16x32_bf16 v[156:159], v[132:135], v[34:37], v[156:159]
	v_mfma_f32_16x16x32_bf16 v[160:163], v[118:121], v[184:187], v[160:163]
	v_mfma_f32_16x16x32_bf16 v[164:167], v[132:135], v[184:187], v[164:167]
	v_mfma_f32_16x16x32_bf16 v[168:171], v[118:121], v[192:195], v[168:171]
	v_mfma_f32_16x16x32_bf16 v[172:175], v[132:135], v[192:195], v[172:175]
	v_mfma_f32_16x16x32_bf16 v[132:135], v[132:135], v[212:215], v[14:17]
	s_setprio 0
	s_setprio 1
	v_mfma_f32_16x16x32_bf16 v[14:17], v[86:89], v[30:33], v[22:25]
	v_mfma_f32_16x16x32_bf16 v[220:223], v[90:93], v[34:37], v[14:17]
	v_mfma_f32_16x16x32_bf16 v[14:17], v[204:207], v[30:33], v[26:29]
	v_mfma_f32_16x16x32_bf16 v[24:27], v[208:211], v[34:37], v[14:17]
	v_mfma_f32_16x16x32_bf16 v[14:17], v[86:89], v[176:179], v[58:61]
	v_mfma_f32_16x16x32_bf16 v[28:31], v[90:93], v[184:187], v[14:17]
	v_mfma_f32_16x16x32_bf16 v[14:17], v[204:207], v[176:179], v[102:105]
	v_mfma_f32_16x16x32_bf16 v[176:179], v[208:211], v[184:187], v[14:17]
	v_mfma_f32_16x16x32_bf16 v[14:17], v[86:89], v[188:191], v[106:109]
	v_mfma_f32_16x16x32_bf16 v[184:187], v[90:93], v[192:195], v[14:17]
	v_mfma_f32_16x16x32_bf16 v[14:17], v[204:207], v[188:191], v[110:113]
	v_mfma_f32_16x16x32_bf16 v[188:191], v[208:211], v[192:195], v[14:17]
	v_mfma_f32_16x16x32_bf16 v[14:17], v[86:89], v[196:199], v[94:97]
	v_mfma_f32_16x16x32_bf16 v[192:195], v[90:93], v[212:215], v[14:17]
	v_mfma_f32_16x16x32_bf16 v[14:17], v[204:207], v[196:199], v[98:101]
	v_mfma_f32_16x16x32_bf16 v[196:199], v[208:211], v[212:215], v[14:17]
	s_setprio 0
	s_barrier
	ds_read_b128 v[204:207], v145
	ds_read_b128 v[208:211], v145 offset:1024
	ds_read_b128 v[212:215], v145 offset:2048
	ds_read_b128 v[224:227], v145 offset:3072
	s_nop 0
	ds_read_b128 v[14:17], v183 offset:32768
	ds_read_b128 v[18:21], v183 offset:33792
	ds_read_b128 v[96:99], v183 offset:34816
	ds_read_b128 v[100:103], v183 offset:35840
	ds_read_b128 v[228:231], v183 offset:36864
	ds_read_b128 v[232:235], v183 offset:37888
	ds_read_b128 v[236:239], v183 offset:38912
	ds_read_b128 v[240:243], v183 offset:39936
	s_waitcnt vmcnt(2)
	s_barrier
	s_waitcnt lgkmcnt(0)
	s_setprio 1
	s_waitcnt lgkmcnt(0)
	v_mfma_f32_16x16x32_bf16 v[0:3], v[204:207], v[14:17], v[0:3]
	v_mfma_f32_16x16x32_bf16 v[104:107], v[208:211], v[18:21], v[0:3]
	v_mfma_f32_16x16x32_bf16 v[0:3], v[212:215], v[14:17], v[62:65]
	v_mfma_f32_16x16x32_bf16 v[108:111], v[224:227], v[18:21], v[0:3]
	v_mfma_f32_16x16x32_bf16 v[0:3], v[204:207], v[96:99], v[66:69]
	v_mfma_f32_16x16x32_bf16 v[88:91], v[208:211], v[100:103], v[0:3]
	v_mfma_f32_16x16x32_bf16 v[0:3], v[212:215], v[96:99], v[70:73]
	v_mfma_f32_16x16x32_bf16 v[92:95], v[224:227], v[100:103], v[0:3]
	v_mfma_f32_16x16x32_bf16 v[0:3], v[204:207], v[228:231], v[74:77]
	v_mfma_f32_16x16x32_bf16 v[56:59], v[208:211], v[232:235], v[0:3]
	v_mfma_f32_16x16x32_bf16 v[0:3], v[212:215], v[228:231], v[78:81]
	v_mfma_f32_16x16x32_bf16 v[60:63], v[224:227], v[232:235], v[0:3]
	v_mfma_f32_16x16x32_bf16 v[0:3], v[204:207], v[236:239], v[82:85]
	v_mfma_f32_16x16x32_bf16 v[32:35], v[208:211], v[240:243], v[0:3]
	v_mfma_f32_16x16x32_bf16 v[0:3], v[212:215], v[236:239], v[200:203]
	v_mfma_f32_16x16x32_bf16 v[36:39], v[224:227], v[240:243], v[0:3]
	s_setprio 0
	s_barrier
	ds_read_b128 v[200:203], v146
	ds_read_b128 v[244:247], v146 offset:1024
	ds_read_b128 v[248:251], v146 offset:2048
	ds_read_b128 v[144:147], v146 offset:3072
	s_waitcnt vmcnt(0)
	s_barrier
	s_waitcnt lgkmcnt(0)
	s_setprio 1
	s_waitcnt lgkmcnt(0)
	v_mfma_f32_16x16x32_bf16 v[0:3], v[200:203], v[14:17], v[10:13]
	v_mfma_f32_16x16x32_bf16 v[120:123], v[244:247], v[18:21], v[0:3]
	v_mfma_f32_16x16x32_bf16 v[0:3], v[248:251], v[14:17], v[136:139]
	v_mfma_f32_16x16x32_bf16 v[124:127], v[144:147], v[18:21], v[0:3]
	v_mfma_f32_16x16x32_bf16 v[0:3], v[200:203], v[96:99], v[140:143]
	v_mfma_f32_16x16x32_bf16 v[112:115], v[244:247], v[100:103], v[0:3]
	v_mfma_f32_16x16x32_bf16 v[0:3], v[248:251], v[96:99], v[152:155]
	v_mfma_f32_16x16x32_bf16 v[116:119], v[144:147], v[100:103], v[0:3]
	v_mfma_f32_16x16x32_bf16 v[0:3], v[200:203], v[228:231], v[40:43]
	v_mfma_f32_16x16x32_bf16 v[96:99], v[244:247], v[232:235], v[0:3]
	v_mfma_f32_16x16x32_bf16 v[0:3], v[248:251], v[228:231], v[44:47]
	v_mfma_f32_16x16x32_bf16 v[100:103], v[144:147], v[232:235], v[0:3]
	v_mfma_f32_16x16x32_bf16 v[0:3], v[200:203], v[236:239], v[48:51]
	v_mfma_f32_16x16x32_bf16 v[64:67], v[244:247], v[240:243], v[0:3]
	v_mfma_f32_16x16x32_bf16 v[0:3], v[248:251], v[236:239], v[52:55]
	v_mfma_f32_16x16x32_bf16 v[68:71], v[144:147], v[240:243], v[0:3]
	s_setprio 0
	s_barrier
	ds_read_b128 v[8:11], v183 offset:49152
	ds_read_b128 v[12:15], v183 offset:50176
	ds_read_b128 v[52:55], v183 offset:51200
	ds_read_b128 v[136:139], v183 offset:52224
	ds_read_b128 v[140:143], v183 offset:53248
	ds_read_b128 v[152:155], v183 offset:54272
	ds_read_b128 v[228:231], v183 offset:55296
	ds_read_b128 v[232:235], v183 offset:56320
	s_barrier
	s_waitcnt lgkmcnt(0)
	s_setprio 1
	s_waitcnt lgkmcnt(0)
	v_mfma_f32_16x16x32_bf16 v[0:3], v[204:207], v[8:11], v[4:7]
	v_mfma_f32_16x16x32_bf16 v[72:75], v[208:211], v[12:15], v[0:3]
	v_mfma_f32_16x16x32_bf16 v[0:3], v[212:215], v[8:11], v[156:159]
	v_mfma_f32_16x16x32_bf16 v[76:79], v[224:227], v[12:15], v[0:3]
	v_mfma_f32_16x16x32_bf16 v[0:3], v[204:207], v[52:55], v[160:163]
	v_mfma_f32_16x16x32_bf16 v[40:43], v[208:211], v[136:139], v[0:3]
	v_mfma_f32_16x16x32_bf16 v[0:3], v[212:215], v[52:55], v[164:167]
	v_mfma_f32_16x16x32_bf16 v[44:47], v[224:227], v[136:139], v[0:3]
	v_mfma_f32_16x16x32_bf16 v[0:3], v[204:207], v[140:143], v[168:171]
	v_mfma_f32_16x16x32_bf16 v[16:19], v[208:211], v[152:155], v[0:3]
	v_mfma_f32_16x16x32_bf16 v[0:3], v[212:215], v[140:143], v[172:175]
	v_mfma_f32_16x16x32_bf16 v[20:23], v[224:227], v[152:155], v[0:3]
	v_mfma_f32_16x16x32_bf16 v[0:3], v[204:207], v[228:231], v[216:219]
	v_mfma_f32_16x16x32_bf16 v[4:7], v[212:215], v[228:231], v[132:135]
	v_mfma_f32_16x16x32_bf16 v[0:3], v[208:211], v[232:235], v[0:3]
	v_mfma_f32_16x16x32_bf16 v[4:7], v[224:227], v[232:235], v[4:7]
	s_setprio 0
	s_setprio 1
	v_mfma_f32_16x16x32_bf16 v[48:51], v[200:203], v[8:11], v[220:223]
	v_mfma_f32_16x16x32_bf16 v[8:11], v[248:251], v[8:11], v[24:27]
	v_mfma_f32_16x16x32_bf16 v[84:87], v[144:147], v[12:15], v[8:11]
	v_mfma_f32_16x16x32_bf16 v[8:11], v[200:203], v[52:55], v[28:31]
	v_mfma_f32_16x16x32_bf16 v[80:83], v[244:247], v[12:15], v[48:51]
	v_mfma_f32_16x16x32_bf16 v[48:51], v[244:247], v[136:139], v[8:11]
	v_mfma_f32_16x16x32_bf16 v[8:11], v[248:251], v[52:55], v[176:179]
	v_mfma_f32_16x16x32_bf16 v[52:55], v[144:147], v[136:139], v[8:11]
	v_mfma_f32_16x16x32_bf16 v[8:11], v[200:203], v[140:143], v[184:187]
	v_mfma_f32_16x16x32_bf16 v[24:27], v[244:247], v[152:155], v[8:11]
	v_mfma_f32_16x16x32_bf16 v[8:11], v[248:251], v[140:143], v[188:191]
	v_mfma_f32_16x16x32_bf16 v[28:31], v[144:147], v[152:155], v[8:11]
	v_mfma_f32_16x16x32_bf16 v[8:11], v[200:203], v[228:231], v[192:195]
	v_mfma_f32_16x16x32_bf16 v[12:15], v[248:251], v[228:231], v[196:199]
	v_mfma_f32_16x16x32_bf16 v[8:11], v[244:247], v[232:235], v[8:11]
	v_mfma_f32_16x16x32_bf16 v[12:15], v[144:147], v[232:235], v[12:15]
	s_setprio 0
	s_cmpk_gt_u32 s0, 0xff
	s_barrier
	s_cbranch_scc1 .LBB0_261
	s_barrier
	s_branch .LBB0_261
